# LN-phase GEMMs: residual-tile loads of the fused LayerNorm epilogue issued before the end-of-loop drain and barrier
# baseline (speedup 1.0000x reference)
; __device__ __forceinline__ f32x4 unpack4(u32x2 u) { return (f32x4){__uint_as_float(u.x << 16), __uint_as_float(u.x & 0xffff0000u), __uint_as_float(u.y << 16), __uint_as_float(u.y & 0xffff0000u)}; }
; #define PG8_WAIT_V(n) asm volatile("s_waitcnt vmcnt(" #n ")" ::: "memory")
; #define PG8_BAR __builtin_amdgcn_s_barrier()
; template <class Epi>
; __device__ __forceinline__ void gemm_phase(LAS unsigned char* lds, const Gemm g, const Sched& S, const Epi& E) {
;     ...
;     PG8_WAIT_V(0);
;     PG8_BAR;
;     __device__ __forceinline__ void fused(f32x4 (&acc)[2][2][4][2], const Unit& u, int wr, int wc, int fr, int fq, LAS unsigned char* lds, int wid, int lane) const {
;     ...
; #pragma unroll
;         for (int ai = 0; ai < 2; ++ai)
; #pragma unroll
;             for (int m = 0; m < 4; ++m) { const size_t off = (size_t)EPI_ROWS(ai, m) * D + col0;
; #pragma unroll
;                 for (int bj = 0; bj < 2; ++bj) { const u32x4 bb = *(const u32x4*)(base + off + bj * HALF);
;                     acc[ai][bj][m][0] = unpack4((u32x2){bb.x, bb.y}) * DN_ALPHA + acc[ai][bj][m][0] * s;
;                     acc[ai][bj][m][1] = unpack4((u32x2){bb.z, bb.w}) * DN_ALPHA + acc[ai][bj][m][1] * s; }
;                 if (m & 1) asm volatile("" ::: "memory"); }
.LBB0_383:
	s_lshl_b32 s2, s47, 5
	s_lshl_b32 s3, s0, 8
	v_lshrrev_b32_e32 v128, 1, v190
	s_or_b32 s2, s3, s2
	s_lshl_b32 s26, s13, 8
	v_and_or_b32 v170, v128, 24, s2
	s_add_i32 s2, s26, s61
	v_or_b32_e32 v192, s2, v191
	v_ashrrev_i32_e32 v193, 31, v192
	v_ashrrev_i32_e32 v171, 31, v170
	v_lshlrev_b64 v[128:129], 11, v[192:193]
	v_lshl_add_u64 v[128:129], s[6:7], 0, v[128:129]
	v_lshlrev_b64 v[168:169], 1, v[170:171]
	v_lshl_add_u64 v[128:129], v[128:129], 0, v[168:169]
	global_load_dwordx4 v[172:175], v[128:129], off
	global_load_dwordx4 v[176:179], v[128:129], off offset:256
	v_or_b32_e32 v128, 16, v192
	v_or_b32_e32 v130, 32, v192
	v_ashrrev_i32_e32 v129, 31, v128
	v_or_b32_e32 v132, 48, v192
	v_add_u32_e32 v134, 0x80, v192
	v_add_u32_e32 v136, 0x90, v192
	v_ashrrev_i32_e32 v131, 31, v130
	v_lshlrev_b64 v[128:129], 11, v[128:129]
	v_ashrrev_i32_e32 v133, 31, v132
	v_ashrrev_i32_e32 v135, 31, v134
	v_ashrrev_i32_e32 v137, 31, v136
	v_lshlrev_b64 v[130:131], 11, v[130:131]
	v_lshl_add_u64 v[128:129], s[6:7], 0, v[128:129]
	v_lshlrev_b64 v[132:133], 11, v[132:133]
	v_lshlrev_b64 v[134:135], 11, v[134:135]
	v_lshlrev_b64 v[136:137], 11, v[136:137]
	v_lshl_add_u64 v[130:131], s[6:7], 0, v[130:131]
	v_lshl_add_u64 v[128:129], v[128:129], 0, v[168:169]
	v_lshl_add_u64 v[132:133], s[6:7], 0, v[132:133]
	v_lshl_add_u64 v[134:135], s[6:7], 0, v[134:135]
	v_lshl_add_u64 v[136:137], s[6:7], 0, v[136:137]
	v_lshl_add_u64 v[130:131], v[130:131], 0, v[168:169]
	global_load_dwordx4 v[164:167], v[128:129], off
	global_load_dwordx4 v[160:163], v[128:129], off offset:256
	v_lshl_add_u64 v[132:133], v[132:133], 0, v[168:169]
	v_lshl_add_u64 v[134:135], v[134:135], 0, v[168:169]
	v_lshl_add_u64 v[180:181], v[136:137], 0, v[168:169]
	global_load_dwordx4 v[156:159], v[130:131], off
	global_load_dwordx4 v[152:155], v[130:131], off offset:256
	global_load_dwordx4 v[148:151], v[132:133], off
	global_load_dwordx4 v[144:147], v[132:133], off offset:256
	s_mov_b32 s2, 0x3f9837f0
	v_add_u32_e32 v194, 0xa0, v192
	global_load_dwordx4 v[140:143], v[134:135], off
	global_load_dwordx4 v[136:139], v[134:135], off offset:256
	s_nop 0
	global_load_dwordx4 v[132:135], v[180:181], off
	global_load_dwordx4 v[128:131], v[180:181], off offset:256
	v_ashrrev_i32_e32 v195, 31, v194
	s_waitcnt vmcnt(0)
	s_barrier
; __device__ __forceinline__ f32x4 unpack4(u32x2 u) { return (f32x4){__uint_as_float(u.x << 16), __uint_as_float(u.x & 0xffff0000u), __uint_as_float(u.y << 16), __uint_as_float(u.y & 0xffff0000u)}; }
;     __device__ __forceinline__ bool run(const f32x4 (&v)[2][2][4][2], const Unit& u, int wr, int wc, int fr, int fq, LAS unsigned char* lds, int wid, int lane) const {
;     ...
;         for (int ai = 0; ai < 2; ++ai)
; #pragma unroll
;             for (int m = 0; m < 4; ++m) {
;                 float s = 0.f;
; #pragma unroll
;                 for (int bj = 0; bj < 2; ++bj)
; #pragma unroll
;                     for (int n = 0; n < 2; ++n) { const f32x4 x = v[ai][bj][m][n]; s += (x[0] + x[1]) + (x[2] + x[3]); }
;                 s += __shfl_xor(s, 16); s += __shfl_xor(s, 32);
;                 const float mw = s * (1.0f / 64.0f); float q = 0.f;
; #pragma unroll
;                 for (int bj = 0; bj < 2; ++bj)
; #pragma unroll
;                     for (int n = 0; n < 2; ++n) { const f32x4 d = v[ai][bj][m][n] - mw; q += (d[0] * d[0] + d[1] * d[1]) + (d[2] * d[2] + d[3] * d[3]); }
;                 q += __shfl_xor(q, 16); q += __shfl_xor(q, 32);
;                 if (fq == 0) P[(ai * HALF + wr * 64 + m * 16 + fr) * 4 + wc] = (f32x2){mw, q};
;     __device__ __forceinline__ void fused(f32x4 (&acc)[2][2][4][2], const Unit& u, int wr, int wc, int fr, int fq, LAS unsigned char* lds, int wid, int lane) const {
;     ...
;             for (int m = 0; m < 4; ++m) { const size_t off = (size_t)EPI_ROWS(ai, m) * D + col0;
; #pragma unroll
;                 for (int bj = 0; bj < 2; ++bj) { const u32x4 bb = *(const u32x4*)(base + off + bj * HALF);
;                     acc[ai][bj][m][0] = unpack4((u32x2){bb.x, bb.y}) * DN_ALPHA + acc[ai][bj][m][0] * s;
;                     acc[ai][bj][m][1] = unpack4((u32x2){bb.z, bb.w}) * DN_ALPHA + acc[ai][bj][m][1] * s; }
;                 if (m & 1) asm volatile("" ::: "memory"); }
	v_lshlrev_b32_e32 v180, 16, v172
	v_and_b32_e32 v181, 0xffff0000, v172
	v_lshlrev_b32_e32 v182, 16, v174
	v_and_b32_e32 v183, 0xffff0000, v174
	v_lshlrev_b32_e32 v174, 16, v175
	v_and_b32_e32 v175, 0xffff0000, v175
	v_lshlrev_b32_e32 v184, 16, v176
	v_and_b32_e32 v185, 0xffff0000, v176
	v_lshlrev_b32_e32 v176, 16, v177
	v_and_b32_e32 v177, 0xffff0000, v177
	v_lshlrev_b32_e32 v186, 16, v178
	v_and_b32_e32 v187, 0xffff0000, v178
	v_pk_mul_f32 v[180:181], v[180:181], s[2:3] op_sel_hi:[1,0]
	v_pk_mul_f32 v[174:175], v[174:175], s[2:3] op_sel_hi:[1,0]
	v_pk_mul_f32 v[176:177], v[176:177], s[2:3] op_sel_hi:[1,0]
	v_pk_mul_f32 v[198:199], v[186:187], s[2:3] op_sel_hi:[1,0]
	v_pk_fma_f32 v[186:187], v[124:125], 0.5, v[180:181] op_sel_hi:[1,0,1]
	v_pk_fma_f32 v[180:181], v[122:123], 0.5, v[174:175] op_sel_hi:[1,0,1]
	v_pk_fma_f32 v[174:175], v[118:119], 0.5, v[176:177] op_sel_hi:[1,0,1]
	v_pk_fma_f32 v[176:177], v[112:113], 0.5, v[198:199] op_sel_hi:[1,0,1]
	v_lshlrev_b64 v[112:113], 11, v[194:195]
	v_lshlrev_b32_e32 v172, 16, v173
	v_and_b32_e32 v173, 0xffff0000, v173
	v_lshl_add_u64 v[112:113], s[6:7], 0, v[112:113]
	v_pk_mul_f32 v[172:173], v[172:173], s[2:3] op_sel_hi:[1,0]
	v_pk_mul_f32 v[182:183], v[182:183], s[2:3] op_sel_hi:[1,0]
	v_lshl_add_u64 v[112:113], v[112:113], 0, v[168:169]
	v_pk_mul_f32 v[196:197], v[184:185], s[2:3] op_sel_hi:[1,0]
	v_pk_fma_f32 v[184:185], v[126:127], 0.5, v[172:173] op_sel_hi:[1,0,1]
	v_pk_fma_f32 v[182:183], v[120:121], 0.5, v[182:183] op_sel_hi:[1,0,1]
	global_load_dwordx4 v[124:127], v[112:113], off
	global_load_dwordx4 v[120:123], v[112:113], off offset:256
	v_add_u32_e32 v112, 0xb0, v192
	v_ashrrev_i32_e32 v113, 31, v112
	v_lshlrev_b64 v[112:113], 11, v[112:113]
	v_lshlrev_b32_e32 v178, 16, v179
	v_and_b32_e32 v179, 0xffff0000, v179
	v_lshl_add_u64 v[112:113], s[6:7], 0, v[112:113]
	v_pk_mul_f32 v[200:201], v[178:179], s[2:3] op_sel_hi:[1,0]
	v_lshl_add_u64 v[112:113], v[112:113], 0, v[168:169]
	v_pk_fma_f32 v[178:179], v[116:117], 0.5, v[196:197] op_sel_hi:[1,0,1]
	v_pk_fma_f32 v[172:173], v[114:115], 0.5, v[200:201] op_sel_hi:[1,0,1]
	global_load_dwordx4 v[116:119], v[112:113], off
	s_nop 0
	global_load_dwordx4 v[112:115], v[112:113], off offset:256
	v_mbcnt_lo_u32_b32 v192, -1, 0
	v_mbcnt_hi_u32_b32 v193, -1, v192
	v_and_b32_e32 v194, 64, v193
	v_add_u32_e32 v203, 64, v194
	v_pk_mov_b32 v[194:195], v[186:187], v[184:185] op_sel:[1,0]
	v_mov_b32_e32 v196, v186
	v_mov_b32_e32 v197, v185
	v_pk_add_f32 v[194:195], v[194:195], v[196:197]
	v_pk_mov_b32 v[196:197], v[182:183], v[180:181] op_sel:[1,0]
	v_mov_b32_e32 v198, v182
	v_mov_b32_e32 v199, v181
	v_pk_add_f32 v[196:197], v[196:197], v[198:199]
	v_add_f32_e32 v194, v194, v195
	v_pk_add_f32 v[196:197], v[196:197], v[196:197] op_sel_hi:[0,1]
	v_xor_b32_e32 v192, 16, v193
	v_add_f32_e32 v195, 0, v194
	v_add_f32_e32 v199, v178, v179
	v_add_f32_e32 v201, v174, v175
	v_mov_b32_e32 v198, v176
	v_mov_b32_e32 v200, v177
	v_mov_b32_e32 v196, v172
	v_mov_b32_e32 v194, v173
	v_cmp_lt_i32_e32 vcc, v192, v203
	v_pk_add_f32 v[198:199], v[198:199], v[200:201]
	v_pk_add_f32 v[194:195], v[196:197], v[194:195]
	v_cndmask_b32_e32 v192, v193, v192, vcc
	v_pk_add_f32 v[194:195], v[198:199], v[194:195]
	v_lshlrev_b32_e32 v192, 2, v192
	v_add_f32_e32 v195, v194, v195
	ds_bpermute_b32 v196, v192, v195
	v_xor_b32_e32 v194, 32, v193
	v_cmp_lt_i32_e32 vcc, v194, v203
	s_lshl_b32 s3, s47, 3
	s_add_i32 s8, s3, 0
	v_cndmask_b32_e32 v193, v193, v194, vcc
	v_lshlrev_b32_e32 v194, 2, v193
	s_waitcnt lgkmcnt(0)
	v_add_f32_e32 v193, v195, v196
	ds_bpermute_b32 v195, v194, v193
	s_waitcnt lgkmcnt(0)
	v_add_f32_e32 v195, v193, v195
	v_fmamk_f32 v196, v195, 0xbc800000, v185
	v_fmamk_f32 v198, v195, 0xbc800000, v187
	v_fmamk_f32 v193, v195, 0xbc800000, v184
	v_fmamk_f32 v197, v195, 0xbc800000, v186
	v_mul_f32_e32 v198, v198, v198
	v_mul_f32_e32 v196, v196, v196
	v_fmac_f32_e32 v198, v197, v197
	v_fmac_f32_e32 v196, v193, v193
	v_fmamk_f32 v197, v195, 0xbc800000, v181
	v_fmamk_f32 v199, v195, 0xbc800000, v183
	v_add_f32_e32 v193, v198, v196
	v_fmamk_f32 v196, v195, 0xbc800000, v180
	v_fmamk_f32 v198, v195, 0xbc800000, v182
	v_mul_f32_e32 v199, v199, v199
	v_mul_f32_e32 v197, v197, v197
	v_fmac_f32_e32 v199, v198, v198
	v_fmac_f32_e32 v197, v196, v196
	v_add_f32_e32 v196, v199, v197
	v_fmamk_f32 v197, v195, 0xbc800000, v175
	v_fmamk_f32 v199, v195, 0xbc800000, v179
	v_add_f32_e32 v193, v193, v196
	v_fmamk_f32 v196, v195, 0xbc800000, v174
	v_fmamk_f32 v198, v195, 0xbc800000, v178
	v_mul_f32_e32 v199, v199, v199
	v_mul_f32_e32 v197, v197, v197
	v_fmac_f32_e32 v199, v198, v198
	v_fmac_f32_e32 v197, v196, v196
	v_add_f32_e32 v196, v199, v197
	v_fmamk_f32 v197, v195, 0xbc800000, v173
	v_fmamk_f32 v199, v195, 0xbc800000, v177
	v_add_f32_e32 v193, v196, v193
	v_fmamk_f32 v196, v195, 0xbc800000, v172
	v_fmamk_f32 v198, v195, 0xbc800000, v176
	v_mul_f32_e32 v199, v199, v199
	v_mul_f32_e32 v197, v197, v197
	v_fmac_f32_e32 v199, v198, v198
	v_fmac_f32_e32 v197, v196, v196
	v_add_f32_e32 v196, v199, v197
	v_add_f32_e32 v196, v196, v193
	ds_bpermute_b32 v197, v192, v196
	v_and_b32_e32 v193, 63, v190
	v_cmp_gt_u32_e32 vcc, 16, v193
	s_waitcnt lgkmcnt(0)
	v_add_f32_e32 v196, v196, v197
	ds_bpermute_b32 v197, v194, v196
	s_and_saveexec_b64 s[4:5], vcc
	s_cbranch_execz .LBB0_385
	s_lshl_b32 s3, s46, 11
	s_add_i32 s3, s8, s3
	v_mul_f32_e32 v198, 0x3c800000, v195
	s_waitcnt lgkmcnt(0)
	v_add_f32_e32 v199, v196, v197
	v_lshl_add_u32 v195, v191, 5, s3
	ds_write_b64 v195, v[198:199]

; __device__ __forceinline__ f32x4 unpack4(u32x2 u) { return (f32x4){__uint_as_float(u.x << 16), __uint_as_float(u.x & 0xffff0000u), __uint_as_float(u.y << 16), __uint_as_float(u.y & 0xffff0000u)}; }
; #define PG8_WAIT_V(n) asm volatile("s_waitcnt vmcnt(" #n ")" ::: "memory")
; #define PG8_BAR __builtin_amdgcn_s_barrier()
; template <class Epi>
; __device__ __forceinline__ void gemm_phase(LAS unsigned char* lds, const Gemm g, const Sched& S, const Epi& E) {
;     ...
;     PG8_WAIT_V(0);
;     PG8_BAR;
;     __device__ __forceinline__ void fused(f32x4 (&acc)[2][2][4][2], const Unit& u, int wr, int wc, int fr, int fq, LAS unsigned char* lds, int wid, int lane) const {
;     ...
;             for (int m = 0; m < 4; ++m) { const size_t off = (size_t)EPI_ROWS(ai, m) * D + col0;
; #pragma unroll
;                 for (int bj = 0; bj < 2; ++bj) { const u32x4 bb = *(const u32x4*)(base + off + bj * HALF);
;                     acc[ai][bj][m][0] = unpack4((u32x2){bb.x, bb.y}) * DN_ALPHA + acc[ai][bj][m][0] * s;
;                     acc[ai][bj][m][1] = unpack4((u32x2){bb.z, bb.w}) * DN_ALPHA + acc[ai][bj][m][1] * s; }
.LBB0_1223:
	s_lshl_b32 s2, s21, 5
	s_lshl_b32 s3, s0, 8
	v_lshrrev_b32_e32 v128, 1, v190
	s_or_b32 s2, s3, s2
	s_lshl_b32 s36, s20, 8
	v_and_or_b32 v178, v128, 24, s2
	s_add_i32 s2, s36, s55
	v_or_b32_e32 v128, s2, v191
	v_ashrrev_i32_e32 v129, 31, v128
	v_ashrrev_i32_e32 v179, 31, v178
	v_lshlrev_b64 v[130:131], 11, v[128:129]
	v_lshl_add_u64 v[130:131], s[14:15], 0, v[130:131]
	v_lshlrev_b64 v[176:177], 1, v[178:179]
	v_lshl_add_u64 v[130:131], v[130:131], 0, v[176:177]
	global_load_dwordx4 v[180:183], v[130:131], off
	global_load_dwordx4 v[184:187], v[130:131], off offset:256
	v_or_b32_e32 v130, 16, v128
	v_or_b32_e32 v132, 32, v128
	v_ashrrev_i32_e32 v131, 31, v130
	v_or_b32_e32 v134, 48, v128
	v_add_u32_e32 v136, 0x80, v128
	v_add_u32_e32 v138, 0x90, v128
	v_add_u32_e32 v140, 0xa0, v128
	v_add_u32_e32 v192, 0xb0, v128
	v_ashrrev_i32_e32 v133, 31, v132
	v_lshlrev_b64 v[128:129], 11, v[130:131]
	v_ashrrev_i32_e32 v135, 31, v134
	v_ashrrev_i32_e32 v137, 31, v136
	v_ashrrev_i32_e32 v139, 31, v138
	v_lshlrev_b64 v[130:131], 11, v[132:133]
	v_lshl_add_u64 v[128:129], s[14:15], 0, v[128:129]
	v_ashrrev_i32_e32 v141, 31, v140
	v_lshlrev_b64 v[132:133], 11, v[134:135]
	v_lshlrev_b64 v[134:135], 11, v[136:137]
	v_lshlrev_b64 v[136:137], 11, v[138:139]
	v_lshl_add_u64 v[130:131], s[14:15], 0, v[130:131]
	v_lshl_add_u64 v[128:129], v[128:129], 0, v[176:177]
	v_lshlrev_b64 v[138:139], 11, v[140:141]
	v_lshl_add_u64 v[132:133], s[14:15], 0, v[132:133]
	v_lshl_add_u64 v[134:135], s[14:15], 0, v[134:135]
	v_lshl_add_u64 v[136:137], s[14:15], 0, v[136:137]
	v_lshl_add_u64 v[130:131], v[130:131], 0, v[176:177]
	global_load_dwordx4 v[172:175], v[128:129], off
	global_load_dwordx4 v[168:171], v[128:129], off offset:256
	v_lshl_add_u64 v[138:139], s[14:15], 0, v[138:139]
	v_lshl_add_u64 v[132:133], v[132:133], 0, v[176:177]
	v_lshl_add_u64 v[134:135], v[134:135], 0, v[176:177]
	v_lshl_add_u64 v[136:137], v[136:137], 0, v[176:177]
	global_load_dwordx4 v[164:167], v[130:131], off
	global_load_dwordx4 v[160:163], v[130:131], off offset:256
	global_load_dwordx4 v[156:159], v[132:133], off
	global_load_dwordx4 v[152:155], v[132:133], off offset:256
	v_lshl_add_u64 v[194:195], v[138:139], 0, v[176:177]
	global_load_dwordx4 v[148:151], v[134:135], off
	global_load_dwordx4 v[144:147], v[134:135], off offset:256
	global_load_dwordx4 v[140:143], v[136:137], off
	s_nop 0
	global_load_dwordx4 v[136:139], v[136:137], off offset:256
	s_mov_b32 s2, 0x3f9837f0
	global_load_dwordx4 v[132:135], v[194:195], off
	global_load_dwordx4 v[128:131], v[194:195], off offset:256
	v_ashrrev_i32_e32 v193, 31, v192
	s_waitcnt vmcnt(0)
	s_barrier
; __device__ __forceinline__ f32x4 unpack4(u32x2 u) { return (f32x4){__uint_as_float(u.x << 16), __uint_as_float(u.x & 0xffff0000u), __uint_as_float(u.y << 16), __uint_as_float(u.y & 0xffff0000u)}; }
;     __device__ __forceinline__ bool run(const f32x4 (&v)[2][2][4][2], const Unit& u, int wr, int wc, int fr, int fq, LAS unsigned char* lds, int wid, int lane) const {
;     ...
;         for (int ai = 0; ai < 2; ++ai)
; #pragma unroll
;             for (int m = 0; m < 4; ++m) {
;                 float s = 0.f;
; #pragma unroll
;                 for (int bj = 0; bj < 2; ++bj)
; #pragma unroll
;                     for (int n = 0; n < 2; ++n) { const f32x4 x = v[ai][bj][m][n]; s += (x[0] + x[1]) + (x[2] + x[3]); }
;                 s += __shfl_xor(s, 16); s += __shfl_xor(s, 32);
;                 const float mw = s * (1.0f / 64.0f); float q = 0.f;
; #pragma unroll
;                 for (int bj = 0; bj < 2; ++bj)
; #pragma unroll
;                     for (int n = 0; n < 2; ++n) { const f32x4 d = v[ai][bj][m][n] - mw; q += (d[0] * d[0] + d[1] * d[1]) + (d[2] * d[2] + d[3] * d[3]); }
;                 q += __shfl_xor(q, 16); q += __shfl_xor(q, 32);
;                 if (fq == 0) P[(ai * HALF + wr * 64 + m * 16 + fr) * 4 + wc] = (f32x2){mw, q};
;     __device__ __forceinline__ void fused(f32x4 (&acc)[2][2][4][2], const Unit& u, int wr, int wc, int fr, int fq, LAS unsigned char* lds, int wid, int lane) const {
;     ...
;             for (int m = 0; m < 4; ++m) { const size_t off = (size_t)EPI_ROWS(ai, m) * D + col0;
; #pragma unroll
;                 for (int bj = 0; bj < 2; ++bj) { const u32x4 bb = *(const u32x4*)(base + off + bj * HALF);
;                     acc[ai][bj][m][0] = unpack4((u32x2){bb.x, bb.y}) * DN_ALPHA + acc[ai][bj][m][0] * s;
;                     acc[ai][bj][m][1] = unpack4((u32x2){bb.z, bb.w}) * DN_ALPHA + acc[ai][bj][m][1] * s; }
;                 if (m & 1) asm volatile("" ::: "memory"); }
	v_lshlrev_b32_e32 v194, 16, v180
	v_and_b32_e32 v195, 0xffff0000, v180
	v_lshlrev_b32_e32 v206, 16, v186
	v_and_b32_e32 v207, 0xffff0000, v186
	v_lshlrev_b32_e32 v208, 16, v187
	v_and_b32_e32 v209, 0xffff0000, v187
	v_pk_fma_f32 v[186:187], v[194:195], s[2:3], v[124:125] op_sel_hi:[1,0,1]
	v_pk_fma_f32 v[124:125], v[206:207], s[2:3], v[112:113] op_sel_hi:[1,0,1]
	v_lshlrev_b64 v[112:113], 11, v[192:193]
	v_lshl_add_u64 v[112:113], s[14:15], 0, v[112:113]
	v_lshlrev_b32_e32 v180, 16, v181
	v_and_b32_e32 v181, 0xffff0000, v181
	v_lshlrev_b32_e32 v196, 16, v182
	v_and_b32_e32 v197, 0xffff0000, v182
	v_lshlrev_b32_e32 v198, 16, v183
	v_and_b32_e32 v199, 0xffff0000, v183
	v_lshlrev_b32_e32 v200, 16, v184
	v_and_b32_e32 v201, 0xffff0000, v184
	v_lshlrev_b32_e32 v204, 16, v185
	v_and_b32_e32 v205, 0xffff0000, v185
	v_lshl_add_u64 v[112:113], v[112:113], 0, v[176:177]
	v_pk_fma_f32 v[184:185], v[180:181], s[2:3], v[126:127] op_sel_hi:[1,0,1]
	v_pk_fma_f32 v[182:183], v[196:197], s[2:3], v[120:121] op_sel_hi:[1,0,1]
	v_pk_fma_f32 v[180:181], v[198:199], s[2:3], v[122:123] op_sel_hi:[1,0,1]
	v_pk_fma_f32 v[126:127], v[200:201], s[2:3], v[116:117] op_sel_hi:[1,0,1]
	v_pk_fma_f32 v[122:123], v[204:205], s[2:3], v[118:119] op_sel_hi:[1,0,1]
	v_pk_fma_f32 v[120:121], v[208:209], s[2:3], v[114:115] op_sel_hi:[1,0,1]
	global_load_dwordx4 v[116:119], v[112:113], off
	s_nop 0
	global_load_dwordx4 v[112:115], v[112:113], off offset:256
	v_mbcnt_lo_u32_b32 v192, -1, 0
	v_mbcnt_hi_u32_b32 v193, -1, v192
	v_and_b32_e32 v194, 64, v193
	v_add_u32_e32 v203, 64, v194
	v_pk_mov_b32 v[194:195], v[186:187], v[184:185] op_sel:[1,0]
	v_mov_b32_e32 v196, v186
	v_mov_b32_e32 v197, v185
	v_pk_add_f32 v[194:195], v[194:195], v[196:197]
	v_pk_mov_b32 v[196:197], v[182:183], v[180:181] op_sel:[1,0]
	v_mov_b32_e32 v198, v182
	v_mov_b32_e32 v199, v181
	v_pk_add_f32 v[196:197], v[196:197], v[198:199]
	v_add_f32_e32 v194, v194, v195
	v_pk_add_f32 v[196:197], v[196:197], v[196:197] op_sel_hi:[0,1]
	v_xor_b32_e32 v192, 16, v193
	v_add_f32_e32 v195, 0, v194
	v_add_f32_e32 v199, v126, v127
	v_add_f32_e32 v201, v122, v123
	v_mov_b32_e32 v198, v124
	v_mov_b32_e32 v200, v125
	v_mov_b32_e32 v196, v120
	v_mov_b32_e32 v194, v121
	v_cmp_lt_i32_e32 vcc, v192, v203
	v_pk_add_f32 v[198:199], v[198:199], v[200:201]
	v_pk_add_f32 v[194:195], v[196:197], v[194:195]
	v_cndmask_b32_e32 v192, v193, v192, vcc
	v_pk_add_f32 v[194:195], v[198:199], v[194:195]
	v_lshlrev_b32_e32 v192, 2, v192
	v_add_f32_e32 v195, v194, v195
	ds_bpermute_b32 v196, v192, v195
	v_xor_b32_e32 v194, 32, v193
	v_cmp_lt_i32_e32 vcc, v194, v203
	s_lshl_b32 s3, s21, 3
	s_add_i32 s21, s3, 0
	v_cndmask_b32_e32 v193, v193, v194, vcc
	v_lshlrev_b32_e32 v194, 2, v193
	s_waitcnt lgkmcnt(0)
	v_add_f32_e32 v193, v195, v196
	ds_bpermute_b32 v195, v194, v193
	s_waitcnt lgkmcnt(0)
	v_add_f32_e32 v195, v193, v195
	v_fmamk_f32 v196, v195, 0xbc800000, v185
	v_fmamk_f32 v198, v195, 0xbc800000, v187
	v_fmamk_f32 v193, v195, 0xbc800000, v184
	v_fmamk_f32 v197, v195, 0xbc800000, v186
	v_mul_f32_e32 v198, v198, v198
	v_mul_f32_e32 v196, v196, v196
	v_fmac_f32_e32 v198, v197, v197
	v_fmac_f32_e32 v196, v193, v193
	v_fmamk_f32 v197, v195, 0xbc800000, v181
	v_fmamk_f32 v199, v195, 0xbc800000, v183
	v_add_f32_e32 v193, v198, v196
	v_fmamk_f32 v196, v195, 0xbc800000, v180
	v_fmamk_f32 v198, v195, 0xbc800000, v182
	v_mul_f32_e32 v199, v199, v199
	v_mul_f32_e32 v197, v197, v197
	v_fmac_f32_e32 v199, v198, v198
	v_fmac_f32_e32 v197, v196, v196
	v_add_f32_e32 v196, v199, v197
	v_fmamk_f32 v197, v195, 0xbc800000, v123
	v_fmamk_f32 v199, v195, 0xbc800000, v127
	v_add_f32_e32 v193, v193, v196
	v_fmamk_f32 v196, v195, 0xbc800000, v122
	v_fmamk_f32 v198, v195, 0xbc800000, v126
	v_mul_f32_e32 v199, v199, v199
	v_mul_f32_e32 v197, v197, v197
	v_fmac_f32_e32 v199, v198, v198
	v_fmac_f32_e32 v197, v196, v196
	v_add_f32_e32 v196, v199, v197
	v_fmamk_f32 v197, v195, 0xbc800000, v121
	v_fmamk_f32 v199, v195, 0xbc800000, v125
	v_add_f32_e32 v193, v196, v193
	v_fmamk_f32 v196, v195, 0xbc800000, v120
	v_fmamk_f32 v198, v195, 0xbc800000, v124
	v_mul_f32_e32 v199, v199, v199
	v_mul_f32_e32 v197, v197, v197
	v_fmac_f32_e32 v199, v198, v198
	v_fmac_f32_e32 v197, v196, v196
	v_add_f32_e32 v196, v199, v197
	v_add_f32_e32 v196, v196, v193
	ds_bpermute_b32 v197, v192, v196
	v_and_b32_e32 v193, 63, v190
	v_cmp_gt_u32_e32 vcc, 16, v193
	s_waitcnt lgkmcnt(0)
	v_add_f32_e32 v196, v196, v197
	ds_bpermute_b32 v197, v194, v196
	s_and_saveexec_b64 s[4:5], vcc
	s_cbranch_execz .LBB0_1225
	s_lshl_b32 s3, s13, 11
	s_add_i32 s3, s21, s3
	v_mul_f32_e32 v198, 0x3c800000, v195
	s_waitcnt lgkmcnt(0)
	v_add_f32_e32 v199, v196, v197
	v_lshl_add_u32 v195, v191, 5, s3
	ds_write_b64 v195, v[198:199]

; __device__ __forceinline__ f32x4 unpack4(u32x2 u) { return (f32x4){__uint_as_float(u.x << 16), __uint_as_float(u.x & 0xffff0000u), __uint_as_float(u.y << 16), __uint_as_float(u.y & 0xffff0000u)}; }
; #define PG8_WAIT_V(n) asm volatile("s_waitcnt vmcnt(" #n ")" ::: "memory")
; #define PG8_BAR __builtin_amdgcn_s_barrier()
; template <class Epi>
; __device__ __forceinline__ void gemm_phase(LAS unsigned char* lds, const Gemm g, const Sched& S, const Epi& E) {
;     ...
;     PG8_WAIT_V(0);
;     PG8_BAR;
;     __device__ __forceinline__ void fused(f32x4 (&acc)[2][2][4][2], const Unit& u, int wr, int wc, int fr, int fq, LAS unsigned char* lds, int wid, int lane) const {
;     ...
;             for (int m = 0; m < 4; ++m) { const size_t off = (size_t)EPI_ROWS(ai, m) * D + col0;
; #pragma unroll
;                 for (int bj = 0; bj < 2; ++bj) { const u32x4 bb = *(const u32x4*)(base + off + bj * HALF);
;                     acc[ai][bj][m][0] = unpack4((u32x2){bb.x, bb.y}) * DN_ALPHA + acc[ai][bj][m][0] * s;
;                     acc[ai][bj][m][1] = unpack4((u32x2){bb.z, bb.w}) * DN_ALPHA + acc[ai][bj][m][1] * s; }
.LBB0_1836:
	s_lshl_b32 s2, s41, 5
	s_lshl_b32 s3, s0, 8
	v_lshrrev_b32_e32 v128, 1, v202
	s_or_b32 s2, s3, s2
	s_lshl_b32 s26, s13, 8
	v_and_or_b32 v168, v128, 24, s2
	s_add_i32 s2, s26, s51
	v_or_b32_e32 v182, s2, v205
	v_ashrrev_i32_e32 v183, 31, v182
	v_ashrrev_i32_e32 v169, 31, v168
	v_lshlrev_b64 v[128:129], 11, v[182:183]
	v_lshl_add_u64 v[128:129], s[14:15], 0, v[128:129]
	v_lshlrev_b64 v[184:185], 1, v[168:169]
	v_lshl_add_u64 v[128:129], v[128:129], 0, v[184:185]
	global_load_dwordx4 v[170:173], v[128:129], off
	global_load_dwordx4 v[174:177], v[128:129], off offset:256
	v_or_b32_e32 v128, 16, v182
	v_or_b32_e32 v130, 32, v182
	v_ashrrev_i32_e32 v129, 31, v128
	v_or_b32_e32 v132, 48, v182
	v_add_u32_e32 v134, 0x80, v182
	v_add_u32_e32 v136, 0x90, v182
	v_ashrrev_i32_e32 v131, 31, v130
	v_lshlrev_b64 v[128:129], 11, v[128:129]
	v_ashrrev_i32_e32 v133, 31, v132
	v_ashrrev_i32_e32 v135, 31, v134
	v_ashrrev_i32_e32 v137, 31, v136
	v_lshlrev_b64 v[130:131], 11, v[130:131]
	v_lshl_add_u64 v[128:129], s[14:15], 0, v[128:129]
	s_mov_b32 s2, 0x3f9837f0
	v_add_u32_e32 v186, 0xa0, v182
	v_lshlrev_b64 v[132:133], 11, v[132:133]
	v_lshlrev_b64 v[134:135], 11, v[134:135]
	v_lshlrev_b64 v[136:137], 11, v[136:137]
	v_lshl_add_u64 v[130:131], s[14:15], 0, v[130:131]
	v_lshl_add_u64 v[128:129], v[128:129], 0, v[184:185]
	v_lshl_add_u64 v[132:133], s[14:15], 0, v[132:133]
	v_lshl_add_u64 v[134:135], s[14:15], 0, v[134:135]
	v_lshl_add_u64 v[136:137], s[14:15], 0, v[136:137]
	v_lshl_add_u64 v[130:131], v[130:131], 0, v[184:185]
	global_load_dwordx4 v[164:167], v[128:129], off
	global_load_dwordx4 v[160:163], v[128:129], off offset:256
	v_ashrrev_i32_e32 v187, 31, v186
	v_lshl_add_u64 v[132:133], v[132:133], 0, v[184:185]
	v_lshl_add_u64 v[134:135], v[134:135], 0, v[184:185]
	v_lshl_add_u64 v[178:179], v[136:137], 0, v[184:185]
	global_load_dwordx4 v[156:159], v[130:131], off
	global_load_dwordx4 v[152:155], v[130:131], off offset:256
	global_load_dwordx4 v[148:151], v[132:133], off
	global_load_dwordx4 v[144:147], v[132:133], off offset:256
	global_load_dwordx4 v[140:143], v[134:135], off
	global_load_dwordx4 v[136:139], v[134:135], off offset:256
	s_nop 0
	global_load_dwordx4 v[132:135], v[178:179], off
	global_load_dwordx4 v[128:131], v[178:179], off offset:256
	v_and_b32_e32 v207, 63, v202
	s_waitcnt vmcnt(0)
	s_barrier
; __device__ __forceinline__ f32x4 unpack4(u32x2 u) { return (f32x4){__uint_as_float(u.x << 16), __uint_as_float(u.x & 0xffff0000u), __uint_as_float(u.y << 16), __uint_as_float(u.y & 0xffff0000u)}; }
;     __device__ __forceinline__ bool run(const f32x4 (&v)[2][2][4][2], const Unit& u, int wr, int wc, int fr, int fq, LAS unsigned char* lds, int wid, int lane) const {
;     ...
;         for (int ai = 0; ai < 2; ++ai)
; #pragma unroll
;             for (int m = 0; m < 4; ++m) {
;                 float s = 0.f;
; #pragma unroll
;                 for (int bj = 0; bj < 2; ++bj)
; #pragma unroll
;                     for (int n = 0; n < 2; ++n) { const f32x4 x = v[ai][bj][m][n]; s += (x[0] + x[1]) + (x[2] + x[3]); }
;                 s += __shfl_xor(s, 16); s += __shfl_xor(s, 32);
;                 const float mw = s * (1.0f / 64.0f); float q = 0.f;
; #pragma unroll
;                 for (int bj = 0; bj < 2; ++bj)
; #pragma unroll
;                     for (int n = 0; n < 2; ++n) { const f32x4 d = v[ai][bj][m][n] - mw; q += (d[0] * d[0] + d[1] * d[1]) + (d[2] * d[2] + d[3] * d[3]); }
;                 q += __shfl_xor(q, 16); q += __shfl_xor(q, 32);
;                 if (fq == 0) P[(ai * HALF + wr * 64 + m * 16 + fr) * 4 + wc] = (f32x2){mw, q};
;     __device__ __forceinline__ void fused(f32x4 (&acc)[2][2][4][2], const Unit& u, int wr, int wc, int fr, int fq, LAS unsigned char* lds, int wid, int lane) const {
;     ...
;             for (int m = 0; m < 4; ++m) { const size_t off = (size_t)EPI_ROWS(ai, m) * D + col0;
; #pragma unroll
;                 for (int bj = 0; bj < 2; ++bj) { const u32x4 bb = *(const u32x4*)(base + off + bj * HALF);
;                     acc[ai][bj][m][0] = unpack4((u32x2){bb.x, bb.y}) * DN_ALPHA + acc[ai][bj][m][0] * s;
;                     acc[ai][bj][m][1] = unpack4((u32x2){bb.z, bb.w}) * DN_ALPHA + acc[ai][bj][m][1] * s; }
;                 if (m & 1) asm volatile("" ::: "memory"); }
	v_lshlrev_b32_e32 v180, 16, v172
	v_and_b32_e32 v181, 0xffff0000, v172
	v_lshlrev_b32_e32 v172, 16, v173
	v_and_b32_e32 v173, 0xffff0000, v173
	v_lshlrev_b32_e32 v190, 16, v176
	v_and_b32_e32 v191, 0xffff0000, v176
	v_pk_mul_f32 v[172:173], v[172:173], s[2:3] op_sel_hi:[1,0]
	v_pk_mul_f32 v[194:195], v[190:191], s[2:3] op_sel_hi:[1,0]
	v_pk_fma_f32 v[198:199], v[122:123], 0.5, v[172:173] op_sel_hi:[1,0,1]
	v_pk_fma_f32 v[172:173], v[112:113], 0.5, v[194:195] op_sel_hi:[1,0,1]
	v_lshlrev_b64 v[112:113], 11, v[186:187]
	v_lshlrev_b32_e32 v178, 16, v170
	v_and_b32_e32 v179, 0xffff0000, v170
	v_lshlrev_b32_e32 v170, 16, v171
	v_and_b32_e32 v171, 0xffff0000, v171
	v_lshl_add_u64 v[112:113], s[14:15], 0, v[112:113]
	v_pk_mul_f32 v[170:171], v[170:171], s[2:3] op_sel_hi:[1,0]
	v_pk_mul_f32 v[178:179], v[178:179], s[2:3] op_sel_hi:[1,0]
	v_pk_mul_f32 v[180:181], v[180:181], s[2:3] op_sel_hi:[1,0]
	v_lshl_add_u64 v[112:113], v[112:113], 0, v[184:185]
	v_pk_fma_f32 v[192:193], v[124:125], 0.5, v[178:179] op_sel_hi:[1,0,1]
	v_pk_fma_f32 v[190:191], v[126:127], 0.5, v[170:171] op_sel_hi:[1,0,1]
	v_pk_fma_f32 v[200:201], v[120:121], 0.5, v[180:181] op_sel_hi:[1,0,1]
	global_load_dwordx4 v[124:127], v[112:113], off
	global_load_dwordx4 v[120:123], v[112:113], off offset:256
	v_add_u32_e32 v112, 0xb0, v182
	v_ashrrev_i32_e32 v113, 31, v112
	v_lshlrev_b64 v[112:113], 11, v[112:113]
	v_lshlrev_b32_e32 v188, 16, v174
	v_and_b32_e32 v189, 0xffff0000, v174
	v_lshlrev_b32_e32 v174, 16, v175
	v_and_b32_e32 v175, 0xffff0000, v175
	v_lshlrev_b32_e32 v176, 16, v177
	v_and_b32_e32 v177, 0xffff0000, v177
	v_lshl_add_u64 v[112:113], s[14:15], 0, v[112:113]
	v_pk_mul_f32 v[174:175], v[174:175], s[2:3] op_sel_hi:[1,0]
	v_pk_mul_f32 v[188:189], v[188:189], s[2:3] op_sel_hi:[1,0]
	v_pk_mul_f32 v[176:177], v[176:177], s[2:3] op_sel_hi:[1,0]
	v_lshl_add_u64 v[112:113], v[112:113], 0, v[184:185]
	v_pk_fma_f32 v[180:181], v[116:117], 0.5, v[188:189] op_sel_hi:[1,0,1]
	v_pk_fma_f32 v[178:179], v[118:119], 0.5, v[174:175] op_sel_hi:[1,0,1]
	v_pk_fma_f32 v[170:171], v[114:115], 0.5, v[176:177] op_sel_hi:[1,0,1]
	global_load_dwordx4 v[116:119], v[112:113], off
	s_nop 0
	global_load_dwordx4 v[112:115], v[112:113], off offset:256
	v_mbcnt_lo_u32_b32 v174, -1, 0
	v_mbcnt_hi_u32_b32 v186, -1, v174
	v_and_b32_e32 v175, 64, v186
	v_xor_b32_e32 v174, 16, v186
	v_add_u32_e32 v187, 64, v175
	v_cmp_lt_i32_e32 vcc, v174, v187
	v_mov_b32_e32 v176, v192
	v_mov_b32_e32 v177, v191
	v_cndmask_b32_e32 v174, v186, v174, vcc
	v_lshlrev_b32_e32 v206, 2, v174
	v_pk_mov_b32 v[174:175], v[192:193], v[190:191] op_sel:[1,0]
	v_mov_b32_e32 v182, v200
	v_pk_add_f32 v[174:175], v[174:175], v[176:177]
	v_pk_mov_b32 v[176:177], v[200:201], v[198:199] op_sel:[1,0]
	v_mov_b32_e32 v183, v199
	v_pk_add_f32 v[176:177], v[176:177], v[182:183]
	v_add_f32_e32 v174, v174, v175
	v_pk_add_f32 v[176:177], v[176:177], v[176:177] op_sel_hi:[0,1]
	v_add_f32_e32 v175, 0, v174
	v_add_f32_e32 v183, v180, v181
	v_add_f32_e32 v185, v178, v179
	v_mov_b32_e32 v182, v172
	v_mov_b32_e32 v184, v173
	v_mov_b32_e32 v176, v170
	v_mov_b32_e32 v174, v171
	v_pk_add_f32 v[182:183], v[182:183], v[184:185]
	v_pk_add_f32 v[174:175], v[176:177], v[174:175]
	v_xor_b32_e32 v176, 32, v186
	v_pk_add_f32 v[174:175], v[182:183], v[174:175]
	v_cmp_lt_i32_e32 vcc, v176, v187
	v_add_f32_e32 v174, v174, v175
	ds_bpermute_b32 v175, v206, v174
	v_cndmask_b32_e32 v176, v186, v176, vcc
	v_lshlrev_b32_e32 v208, 2, v176
	s_lshl_b32 s3, s41, 3
	s_waitcnt lgkmcnt(0)
	v_add_f32_e32 v174, v174, v175
	ds_bpermute_b32 v175, v208, v174
	v_cmp_gt_u32_e32 vcc, 16, v207
	s_add_i32 s16, s3, 0
	s_waitcnt lgkmcnt(0)
	v_add_f32_e32 v174, v174, v175
	v_fmamk_f32 v176, v174, 0xbc800000, v191
	v_fmamk_f32 v182, v174, 0xbc800000, v193
	v_fmamk_f32 v175, v174, 0xbc800000, v190
	v_fmamk_f32 v177, v174, 0xbc800000, v192
	v_mul_f32_e32 v182, v182, v182
	v_mul_f32_e32 v176, v176, v176
	v_fmac_f32_e32 v182, v177, v177
	v_fmac_f32_e32 v176, v175, v175
	v_fmamk_f32 v177, v174, 0xbc800000, v199
	v_fmamk_f32 v183, v174, 0xbc800000, v201
	v_add_f32_e32 v175, v182, v176
	v_fmamk_f32 v176, v174, 0xbc800000, v198
	v_fmamk_f32 v182, v174, 0xbc800000, v200
	v_mul_f32_e32 v183, v183, v183
	v_mul_f32_e32 v177, v177, v177
	v_fmac_f32_e32 v183, v182, v182
	v_fmac_f32_e32 v177, v176, v176
	v_add_f32_e32 v176, v183, v177
	v_fmamk_f32 v177, v174, 0xbc800000, v179
	v_fmamk_f32 v183, v174, 0xbc800000, v181
	v_add_f32_e32 v175, v175, v176
	v_fmamk_f32 v176, v174, 0xbc800000, v178
	v_fmamk_f32 v182, v174, 0xbc800000, v180
	v_mul_f32_e32 v183, v183, v183
	v_mul_f32_e32 v177, v177, v177
	v_fmac_f32_e32 v183, v182, v182
	v_fmac_f32_e32 v177, v176, v176
	v_add_f32_e32 v176, v183, v177
	v_fmamk_f32 v177, v174, 0xbc800000, v171
	v_fmamk_f32 v183, v174, 0xbc800000, v173
	v_add_f32_e32 v175, v176, v175
	v_fmamk_f32 v176, v174, 0xbc800000, v170
	v_fmamk_f32 v182, v174, 0xbc800000, v172
	v_mul_f32_e32 v183, v183, v183
	v_mul_f32_e32 v177, v177, v177
	v_fmac_f32_e32 v183, v182, v182
	v_fmac_f32_e32 v177, v176, v176
	v_add_f32_e32 v176, v183, v177
	v_add_f32_e32 v175, v176, v175
	ds_bpermute_b32 v176, v206, v175
	s_waitcnt lgkmcnt(0)
	v_add_f32_e32 v175, v175, v176
	ds_bpermute_b32 v176, v208, v175
	s_and_saveexec_b64 s[4:5], vcc
	s_cbranch_execz .LBB0_1838
	s_lshl_b32 s3, s40, 11
	s_add_i32 s3, s16, s3
	v_mul_f32_e32 v174, 0x3c800000, v174
	s_waitcnt lgkmcnt(0)
	v_add_f32_e32 v175, v175, v176
	v_lshl_add_u32 v176, v205, 5, s3
	ds_write_b64 v176, v[174:175]
